# v17 + out-proj/FFN-out GEMM phases: blocks 0..191 (no sample-row unit) start ~3us late (s_sleep 96) so their epilogue store burst does not coincide with that of blocks 192..255, which still have a sam
# speedup vs baseline: 1.0111x; 1.0026x over previous
.LBB0_1158:
	s_cmpk_lt_u32 s2, 0xc0
	s_cbranch_scc0 .Lg1_nodelay
	s_sleep 96
